# GEMM epilogues (in-proj, FFN2 gate-up): row sums requested before the K loop, head-of-epilogue vmcnt(0) removed
# speedup vs baseline: 1.0181x; 1.0170x over previous
; template <class Epi, class Sched, bool ALIGN_EPI = false, bool SP2 = false>
; __device__ __forceinline__ void gemm_phase(LAS unsigned char* lds, const Gemm g, const Sched S, const Epi E) {
;     ...
; #pragma unroll
;         for (int a = 0; a < 2; ++a)
; #pragma unroll
;             for (int b = 0; b < 2; ++b)
; #pragma unroll
;                 for (int m = 0; m < 4; ++m)
; #pragma unroll
;                     for (int n = 0; n < 2; ++n) acc[a][b][m][n] = (f32x4){0.f, 0.f, 0.f, 0.f};
;         cur = nxt; cA = nA; cB = nB; ++ui;
.LBB0_790:
	s_ashr_i32 s63, s62, 31
	s_lshl_b64 s[34:35], s[62:63], 20
	s_add_u32 s66, s24, s34
	s_addc_u32 s67, s25, s35
	s_and_b64 s[34:35], s[8:9], exec
	s_cselect_b32 s11, s67, s73
	s_cselect_b32 s63, s66, s72
	s_ashr_i32 s61, s60, 31
	s_lshl_b64 s[34:35], s[60:61], 19
	s_add_u32 s68, s18, s34
	s_addc_u32 s69, s19, s35
	s_and_b64 s[34:35], s[8:9], exec
	s_cselect_b32 s61, s69, s75
	s_cselect_b32 s71, s68, s74
	s_add_u32 s72, s72, 0x80080
	s_addc_u32 s73, s73, 0
	s_add_u32 s86, s74, 0x100
	v_mov_b32_e32 v0, 0
	s_addc_u32 s87, s75, 0
	s_mov_b32 s88, -2
	v_mov_b32_e32 v1, v0
	v_mov_b32_e32 v2, v0
	v_mov_b32_e32 v3, v0
	v_mov_b32_e32 v4, v0
	v_mov_b32_e32 v5, v0
	v_mov_b32_e32 v6, v0
	v_mov_b32_e32 v7, v0
	v_mov_b32_e32 v16, v0
	v_mov_b32_e32 v17, v0
	v_mov_b32_e32 v18, v0
	v_mov_b32_e32 v19, v0
	v_mov_b32_e32 v20, v0
	v_mov_b32_e32 v21, v0
	v_mov_b32_e32 v22, v0
	v_mov_b32_e32 v23, v0
	v_mov_b32_e32 v32, v0
	v_mov_b32_e32 v33, v0
	v_mov_b32_e32 v34, v0
	v_mov_b32_e32 v35, v0
	v_mov_b32_e32 v36, v0
	v_mov_b32_e32 v37, v0
	v_mov_b32_e32 v38, v0
	v_mov_b32_e32 v39, v0
	v_mov_b32_e32 v48, v0
	v_mov_b32_e32 v49, v0
	v_mov_b32_e32 v50, v0
	v_mov_b32_e32 v51, v0
	v_mov_b32_e32 v52, v0
	v_mov_b32_e32 v53, v0
	v_mov_b32_e32 v54, v0
	v_mov_b32_e32 v55, v0
	v_mov_b32_e32 v8, v0
	v_mov_b32_e32 v9, v0
	v_mov_b32_e32 v10, v0
	v_mov_b32_e32 v11, v0
	v_mov_b32_e32 v12, v0
	v_mov_b32_e32 v13, v0
	v_mov_b32_e32 v14, v0
	v_mov_b32_e32 v15, v0
	v_mov_b32_e32 v24, v0
	v_mov_b32_e32 v25, v0
	v_mov_b32_e32 v26, v0
	v_mov_b32_e32 v27, v0
	v_mov_b32_e32 v28, v0
	v_mov_b32_e32 v29, v0
	v_mov_b32_e32 v30, v0
	v_mov_b32_e32 v31, v0
	v_mov_b32_e32 v40, v0
	v_mov_b32_e32 v41, v0
	v_mov_b32_e32 v42, v0
	v_mov_b32_e32 v43, v0
	v_mov_b32_e32 v44, v0
	v_mov_b32_e32 v45, v0
	v_mov_b32_e32 v46, v0
	v_mov_b32_e32 v47, v0
	v_mov_b32_e32 v56, v0
	v_mov_b32_e32 v57, v0
	v_mov_b32_e32 v58, v0
	v_mov_b32_e32 v59, v0
	v_mov_b32_e32 v60, v0
	v_mov_b32_e32 v61, v0
	v_mov_b32_e32 v62, v0
	v_mov_b32_e32 v63, v0
	v_mov_b32_e32 v64, v0
	v_mov_b32_e32 v65, v0
	v_mov_b32_e32 v66, v0
	v_mov_b32_e32 v67, v0
	v_mov_b32_e32 v68, v0
	v_mov_b32_e32 v69, v0
	v_mov_b32_e32 v70, v0
	v_mov_b32_e32 v71, v0
	v_mov_b32_e32 v80, v0
	v_mov_b32_e32 v81, v0
	v_mov_b32_e32 v82, v0
	v_mov_b32_e32 v83, v0
	v_mov_b32_e32 v84, v0
	v_mov_b32_e32 v85, v0
	v_mov_b32_e32 v86, v0
	v_mov_b32_e32 v87, v0
	v_mov_b32_e32 v96, v0
	v_mov_b32_e32 v97, v0
	v_mov_b32_e32 v98, v0
	v_mov_b32_e32 v99, v0
	v_mov_b32_e32 v100, v0
	v_mov_b32_e32 v101, v0
	v_mov_b32_e32 v102, v0
	v_mov_b32_e32 v103, v0
	v_mov_b32_e32 v112, v0
	v_mov_b32_e32 v113, v0
	v_mov_b32_e32 v114, v0
	v_mov_b32_e32 v115, v0
	v_mov_b32_e32 v116, v0
	v_mov_b32_e32 v117, v0
	v_mov_b32_e32 v118, v0
	v_mov_b32_e32 v119, v0
	v_mov_b32_e32 v72, v0
	v_mov_b32_e32 v73, v0
	v_mov_b32_e32 v74, v0
	v_mov_b32_e32 v75, v0
	v_mov_b32_e32 v76, v0
	v_mov_b32_e32 v77, v0
	v_mov_b32_e32 v78, v0
	v_mov_b32_e32 v79, v0
	v_mov_b32_e32 v88, v0
	v_mov_b32_e32 v89, v0
	v_mov_b32_e32 v90, v0
	v_mov_b32_e32 v91, v0
	v_mov_b32_e32 v92, v0
	v_mov_b32_e32 v93, v0
	v_mov_b32_e32 v94, v0
	v_mov_b32_e32 v95, v0
	v_mov_b32_e32 v104, v0
	v_mov_b32_e32 v105, v0
	v_mov_b32_e32 v106, v0
	v_mov_b32_e32 v107, v0
	v_mov_b32_e32 v108, v0
	v_mov_b32_e32 v109, v0
	v_mov_b32_e32 v110, v0
	v_mov_b32_e32 v111, v0
	v_mov_b32_e32 v120, v0
	v_mov_b32_e32 v121, v0
	v_mov_b32_e32 v122, v0
	v_mov_b32_e32 v123, v0
	v_mov_b32_e32 v124, v0
	v_mov_b32_e32 v125, v0
	v_mov_b32_e32 v126, v0
	v_mov_b32_e32 v127, v0
	s_lshl_b32 s100, s10, 8
	s_add_i32 s100, s100, s31
	v_or_b32_e32 v252, s100, v150
	v_ashrrev_i32_e32 v253, 31, v252
	v_lshl_add_u64 v[252:253], v[252:253], 2, s[26:27]
	global_load_dword v244, v[252:253], off
	global_load_dword v245, v[252:253], off offset:64
	global_load_dword v246, v[252:253], off offset:128
	global_load_dword v247, v[252:253], off offset:192
	global_load_dword v248, v[252:253], off offset:512
	global_load_dword v249, v[252:253], off offset:576
	global_load_dword v250, v[252:253], off offset:640
	global_load_dword v251, v[252:253], off offset:704

.LBB0_794:
	s_lshl_b32 s61, s10, 8
	s_add_i32 s61, s61, s31
	v_or_b32_e32 v148, s61, v150
	v_ashrrev_i32_e32 v149, 31, v148
	v_lshl_add_u64 v[146:147], v[148:149], 2, s[26:27]
	v_mov_b32_e32 v165, v244
	v_mov_b32_e32 v164, v245
	v_mov_b32_e32 v163, v246
	v_mov_b32_e32 v162, v247
	v_mov_b32_e32 v161, v248
	v_mov_b32_e32 v160, v249
	v_mov_b32_e32 v159, v250
	v_mov_b32_e32 v158, v251
	v_lshl_or_b32 v146, s70, 8, v152
	v_mov_b64_e32 v[166:167], s[40:41]
	v_bitop3_b32 v169, v146, -16, v157 bitop3:0xc8
	v_ashrrev_i32_e32 v147, 31, v146
	v_mad_i64_i32 v[166:167], s[10:11], v148, s83, v[166:167]
	v_lshl_add_u64 v[166:167], v[146:147], 1, v[166:167]
	v_cmp_eq_u32_e64 s[10:11], s84, v169
	v_fmamk_f32 v165, v165, 0x3a800000, v156
	v_mul_f32_e32 v168, 0x4b800000, v165
	v_cmp_gt_f32_e32 vcc, s82, v165
	s_nop 1
	v_cndmask_b32_e32 v165, v165, v168, vcc
	v_rsq_f32_e32 v165, v165
	s_nop 0
	v_mul_f32_e32 v168, 0x45800000, v165
	v_cndmask_b32_e32 v168, v165, v168, vcc
	v_pk_mul_f32 v[126:127], v[126:127], v[168:169] op_sel_hi:[1,0]
	v_pk_mul_f32 v[124:125], v[124:125], v[168:169] op_sel_hi:[1,0]
	v_pk_mul_f32 v[170:171], v[122:123], v[168:169] op_sel_hi:[1,0]
	v_pk_mul_f32 v[122:123], v[120:121], v[168:169] op_sel_hi:[1,0]
	v_pk_mul_f32 v[118:119], v[118:119], v[168:169] op_sel_hi:[1,0]
	v_pk_mul_f32 v[116:117], v[116:117], v[168:169] op_sel_hi:[1,0]
	v_pk_mul_f32 v[114:115], v[114:115], v[168:169] op_sel_hi:[1,0]
	v_pk_mul_f32 v[112:113], v[112:113], v[168:169] op_sel_hi:[1,0]
	v_cvt_pk_bf16_f32 v120, v124, v125
	v_cvt_pk_bf16_f32 v121, v126, v127
	v_cvt_pk_bf16_f32 v122, v122, v123
	v_cvt_pk_bf16_f32 v123, v170, v171
	v_cvt_pk_bf16_f32 v124, v116, v117
	v_cvt_pk_bf16_f32 v125, v118, v119
	v_cvt_pk_bf16_f32 v126, v112, v113
	v_cvt_pk_bf16_f32 v127, v114, v115
	global_store_dwordx4 v[166:167], v[120:123], off
	global_store_dwordx4 v[166:167], v[124:127], off offset:256
	s_and_saveexec_b64 s[72:73], s[10:11]
	s_cbranch_execz .LBB0_796
	v_lshlrev_b64 v[120:121], 6, v[148:149]
	v_lshl_add_u64 v[120:121], s[64:65], 0, v[120:121]
	v_lshl_add_u64 v[120:121], v[146:147], 2, v[120:121]
	v_add_co_u32_e32 v120, vcc, 0xffffc000, v120
	s_nop 1
	v_addc_co_u32_e32 v121, vcc, -1, v121, vcc
	global_store_dwordx4 v[120:121], v[116:119], off offset:-2304
	global_store_dwordx4 v[120:121], v[112:115], off offset:-2288

; template <class Epi, class Sched, bool ALIGN_EPI = false, bool SP2 = false>
; __device__ __forceinline__ void gemm_phase(LAS unsigned char* lds, const Gemm g, const Sched S, const Epi E) {
;     ...
; #pragma unroll
;         for (int a = 0; a < 2; ++a)
; #pragma unroll
;             for (int b = 0; b < 2; ++b)
; #pragma unroll
;                 for (int m = 0; m < 4; ++m)
; #pragma unroll
;                     for (int n = 0; n < 2; ++n) acc[a][b][m][n] = (f32x4){0.f, 0.f, 0.f, 0.f};
;         cur = nxt; cA = nA; cB = nB; ++ui;
.LBB0_1849:
	s_ashr_i32 s53, s52, 31
	s_lshl_b64 s[14:15], s[52:53], 20
	s_add_u32 s54, s24, s14
	s_addc_u32 s55, s25, s15
	s_and_b64 s[14:15], s[6:7], exec
	s_cselect_b32 s16, s55, s11
	s_cselect_b32 s17, s54, s10
	s_ashr_i32 s51, s50, 31
	s_lshl_b64 s[14:15], s[50:51], 19
	s_add_u32 s56, s38, s14
	s_addc_u32 s57, s39, s15
	s_and_b64 s[14:15], s[6:7], exec
	s_cselect_b32 s18, s57, s13
	s_cselect_b32 s19, s56, s12
	s_add_u32 s10, s10, 0x80080
	s_addc_u32 s11, s11, 0
	s_add_u32 s22, s12, 0x100
	v_mov_b32_e32 v0, 0
	s_addc_u32 s23, s13, 0
	s_mov_b32 s51, -2
	v_mov_b32_e32 v1, v0
	v_mov_b32_e32 v2, v0
	v_mov_b32_e32 v3, v0
	v_mov_b32_e32 v4, v0
	v_mov_b32_e32 v5, v0
	v_mov_b32_e32 v6, v0
	v_mov_b32_e32 v7, v0
	v_mov_b32_e32 v16, v0
	v_mov_b32_e32 v17, v0
	v_mov_b32_e32 v18, v0
	v_mov_b32_e32 v19, v0
	v_mov_b32_e32 v20, v0
	v_mov_b32_e32 v21, v0
	v_mov_b32_e32 v22, v0
	v_mov_b32_e32 v23, v0
	v_mov_b32_e32 v32, v0
	v_mov_b32_e32 v33, v0
	v_mov_b32_e32 v34, v0
	v_mov_b32_e32 v35, v0
	v_mov_b32_e32 v36, v0
	v_mov_b32_e32 v37, v0
	v_mov_b32_e32 v38, v0
	v_mov_b32_e32 v39, v0
	v_mov_b32_e32 v48, v0
	v_mov_b32_e32 v49, v0
	v_mov_b32_e32 v50, v0
	v_mov_b32_e32 v51, v0
	v_mov_b32_e32 v52, v0
	v_mov_b32_e32 v53, v0
	v_mov_b32_e32 v54, v0
	v_mov_b32_e32 v55, v0
	v_mov_b32_e32 v8, v0
	v_mov_b32_e32 v9, v0
	v_mov_b32_e32 v10, v0
	v_mov_b32_e32 v11, v0
	v_mov_b32_e32 v12, v0
	v_mov_b32_e32 v13, v0
	v_mov_b32_e32 v14, v0
	v_mov_b32_e32 v15, v0
	v_mov_b32_e32 v24, v0
	v_mov_b32_e32 v25, v0
	v_mov_b32_e32 v26, v0
	v_mov_b32_e32 v27, v0
	v_mov_b32_e32 v28, v0
	v_mov_b32_e32 v29, v0
	v_mov_b32_e32 v30, v0
	v_mov_b32_e32 v31, v0
	v_mov_b32_e32 v40, v0
	v_mov_b32_e32 v41, v0
	v_mov_b32_e32 v42, v0
	v_mov_b32_e32 v43, v0
	v_mov_b32_e32 v44, v0
	v_mov_b32_e32 v45, v0
	v_mov_b32_e32 v46, v0
	v_mov_b32_e32 v47, v0
	v_mov_b32_e32 v56, v0
	v_mov_b32_e32 v57, v0
	v_mov_b32_e32 v58, v0
	v_mov_b32_e32 v59, v0
	v_mov_b32_e32 v60, v0
	v_mov_b32_e32 v61, v0
	v_mov_b32_e32 v62, v0
	v_mov_b32_e32 v63, v0
	v_mov_b32_e32 v64, v0
	v_mov_b32_e32 v65, v0
	v_mov_b32_e32 v66, v0
	v_mov_b32_e32 v67, v0
	v_mov_b32_e32 v68, v0
	v_mov_b32_e32 v69, v0
	v_mov_b32_e32 v70, v0
	v_mov_b32_e32 v71, v0
	v_mov_b32_e32 v80, v0
	v_mov_b32_e32 v81, v0
	v_mov_b32_e32 v82, v0
	v_mov_b32_e32 v83, v0
	v_mov_b32_e32 v84, v0
	v_mov_b32_e32 v85, v0
	v_mov_b32_e32 v86, v0
	v_mov_b32_e32 v87, v0
	v_mov_b32_e32 v96, v0
	v_mov_b32_e32 v97, v0
	v_mov_b32_e32 v98, v0
	v_mov_b32_e32 v99, v0
	v_mov_b32_e32 v100, v0
	v_mov_b32_e32 v101, v0
	v_mov_b32_e32 v102, v0
	v_mov_b32_e32 v103, v0
	v_mov_b32_e32 v112, v0
	v_mov_b32_e32 v113, v0
	v_mov_b32_e32 v114, v0
	v_mov_b32_e32 v115, v0
	v_mov_b32_e32 v116, v0
	v_mov_b32_e32 v117, v0
	v_mov_b32_e32 v118, v0
	v_mov_b32_e32 v119, v0
	v_mov_b32_e32 v72, v0
	v_mov_b32_e32 v73, v0
	v_mov_b32_e32 v74, v0
	v_mov_b32_e32 v75, v0
	v_mov_b32_e32 v76, v0
	v_mov_b32_e32 v77, v0
	v_mov_b32_e32 v78, v0
	v_mov_b32_e32 v79, v0
	v_mov_b32_e32 v88, v0
	v_mov_b32_e32 v89, v0
	v_mov_b32_e32 v90, v0
	v_mov_b32_e32 v91, v0
	v_mov_b32_e32 v92, v0
	v_mov_b32_e32 v93, v0
	v_mov_b32_e32 v94, v0
	v_mov_b32_e32 v95, v0
	v_mov_b32_e32 v104, v0
	v_mov_b32_e32 v105, v0
	v_mov_b32_e32 v106, v0
	v_mov_b32_e32 v107, v0
	v_mov_b32_e32 v108, v0
	v_mov_b32_e32 v109, v0
	v_mov_b32_e32 v110, v0
	v_mov_b32_e32 v111, v0
	v_mov_b32_e32 v120, v0
	v_mov_b32_e32 v121, v0
	v_mov_b32_e32 v122, v0
	v_mov_b32_e32 v123, v0
	v_mov_b32_e32 v124, v0
	v_mov_b32_e32 v125, v0
	v_mov_b32_e32 v126, v0
	v_mov_b32_e32 v127, v0
	v_lshl_add_u32 v252, s8, 8, v147
	v_ashrrev_i32_e32 v253, 31, v252
	v_lshl_add_u64 v[254:255], v[252:253], 2, s[42:43]
	global_load_dword v244, v[254:255], off
	global_load_dword v245, v[254:255], off offset:512
	global_load_dword v246, v[254:255], off offset:576
	global_load_dword v247, v[254:255], off offset:640
	global_load_dword v248, v[254:255], off offset:64
	global_load_dword v249, v[254:255], off offset:128
	global_load_dword v250, v[254:255], off offset:192
	global_load_dword v251, v[254:255], off offset:704

.LBB0_1853:
	v_lshl_add_u32 v166, s8, 8, v147
	v_ashrrev_i32_e32 v167, 31, v166
	v_or_b32_e32 v160, 16, v166
	v_lshl_add_u64 v[144:145], v[166:167], 2, s[42:43]
	v_ashrrev_i32_e32 v161, 31, v160
	v_or_b32_e32 v156, 32, v166
	v_or_b32_e32 v152, 48, v166
	v_lshl_add_u64 v[168:169], v[160:161], 2, s[42:43]
	v_ashrrev_i32_e32 v157, 31, v156
	v_ashrrev_i32_e32 v153, 31, v152
	v_mov_b32_e32 v146, v244
	v_mov_b32_e32 v148, v245
	v_mov_b32_e32 v150, v246
	v_mov_b32_e32 v154, v247
	v_lshl_add_u64 v[170:171], v[156:157], 2, s[42:43]
	v_lshl_add_u64 v[172:173], v[152:153], 2, s[42:43]
	v_mov_b32_e32 v158, v248
	v_mov_b32_e32 v162, v249
	v_mov_b32_e32 v167, v250
	s_nop 0
	v_mov_b32_e32 v168, v251
	v_lshl_or_b32 v144, s9, 7, v151
	v_ashrrev_i32_e32 v145, 31, v144
	v_lshl_add_u64 v[144:145], v[144:145], 1, s[40:41]
	v_add_u32_e32 v165, 0x80, v166
	v_add_u32_e32 v161, 0x90, v166
	v_add_u32_e32 v157, 0xa0, v166
	v_add_u32_e32 v153, 0xb0, v166
	v_fmamk_f32 v146, v146, 0x3a800000, v164
	v_fmamk_f32 v148, v148, 0x3a800000, v164
	v_mul_f32_e32 v169, 0x4b800000, v146
	v_fmamk_f32 v154, v154, 0x3a800000, v164
	v_fmamk_f32 v158, v158, 0x3a800000, v164
	v_mul_f32_e32 v170, 0x4b800000, v148
	v_mul_f32_e32 v172, 0x4b800000, v154
	v_fmamk_f32 v168, v168, 0x3a800000, v164
	v_cmp_gt_f32_e32 vcc, s63, v146
	v_cmp_gt_f32_e64 s[8:9], s63, v148
	v_cmp_gt_f32_e64 s[12:13], s63, v154
	v_fmamk_f32 v150, v150, 0x3a800000, v164
	v_fmamk_f32 v167, v167, 0x3a800000, v164
	v_cndmask_b32_e32 v146, v146, v169, vcc
	v_mul_f32_e32 v169, 0x4b800000, v158
	v_cndmask_b32_e64 v148, v148, v170, s[8:9]
	v_cndmask_b32_e64 v154, v154, v172, s[12:13]
	v_mul_f32_e32 v170, 0x4b800000, v168
	v_cmp_gt_f32_e64 s[14:15], s63, v158
	v_cmp_gt_f32_e64 s[22:23], s63, v168
	v_mul_f32_e32 v171, 0x4b800000, v150
	v_mul_f32_e32 v174, 0x4b800000, v167
	v_cmp_gt_f32_e64 s[10:11], s63, v150
	v_rsq_f32_e32 v146, v146
	v_cndmask_b32_e64 v158, v158, v169, s[14:15]
	v_cmp_gt_f32_e64 s[18:19], s63, v167
	v_rsq_f32_e32 v148, v148
	v_rsq_f32_e32 v169, v154
	v_cndmask_b32_e64 v154, v168, v170, s[22:23]
	v_cndmask_b32_e64 v150, v150, v171, s[10:11]
	v_cndmask_b32_e64 v167, v167, v174, s[18:19]
	v_rsq_f32_e32 v171, v154
	v_fmamk_f32 v162, v162, 0x3a800000, v164
	v_rsq_f32_e32 v158, v158
	v_rsq_f32_e32 v167, v167
	v_mul_f32_e32 v173, 0x4b800000, v162
	v_cmp_gt_f32_e64 s[16:17], s63, v162
	v_rsq_f32_e32 v150, v150
	v_mul_f32_e32 v154, 0x45800000, v146
	v_cndmask_b32_e64 v162, v162, v173, s[16:17]
	v_mul_f32_e32 v170, 0x45800000, v148
	v_mul_f32_e32 v173, 0x45800000, v169
	v_cndmask_b32_e32 v168, v146, v154, vcc
	v_cndmask_b32_e64 v154, v148, v170, s[8:9]
	v_cndmask_b32_e64 v148, v169, v173, s[12:13]
	v_mul_f32_e32 v169, 0x45800000, v171
	v_mul_f32_e32 v146, 0x45800000, v158
	v_mul_f32_e32 v175, 0x45800000, v167
	v_pk_mul_f32 v[124:125], v[124:125], v[168:169] op_sel_hi:[1,0]
	v_mul_f32_e32 v172, 0x45800000, v150
	v_cndmask_b32_e64 v170, v158, v146, s[14:15]
	v_cndmask_b32_e64 v158, v167, v175, s[18:19]
	v_cndmask_b32_e64 v146, v171, v169, s[22:23]
	v_pk_mul_f32 v[120:121], v[120:121], v[168:169] op_sel_hi:[1,0]
	v_mul_f32_e32 v167, 0xbfb8aa3b, v124
	v_mul_f32_e32 v169, 0xbfb8aa3b, v125
	v_cndmask_b32_e64 v150, v150, v172, s[10:11]
	v_mul_f32_e32 v172, 0xbfb8aa3b, v121
	v_exp_f32_e32 v167, v167
	v_exp_f32_e32 v169, v169
	v_exp_f32_e32 v172, v172
	v_mul_f32_e32 v171, 0xbfb8aa3b, v120
	v_add_f32_e32 v167, 1.0, v167
	v_add_f32_e32 v169, 1.0, v169
	v_add_f32_e32 v175, 1.0, v172
	v_rcp_f32_e32 v172, v167
	v_rcp_f32_e32 v173, v169
	v_rsq_f32_e32 v162, v162
	v_exp_f32_e32 v171, v171
	v_pk_mul_f32 v[116:117], v[116:117], v[168:169] op_sel_hi:[1,0]
	v_pk_mul_f32 v[124:125], v[124:125], v[172:173]
	v_mul_f32_e32 v174, 0x45800000, v162
	v_add_f32_e32 v171, 1.0, v171
	v_pk_mul_f32 v[116:117], v[116:117], v[124:125]
	v_pk_mul_f32 v[124:125], v[126:127], v[168:169] op_sel_hi:[1,0]
	v_cndmask_b32_e64 v162, v162, v174, s[16:17]
	v_rcp_f32_e32 v174, v171
	v_rcp_f32_e32 v175, v175
	v_mul_f32_e32 v126, 0xbfb8aa3b, v124
	v_mul_f32_e32 v127, 0xbfb8aa3b, v125
	v_exp_f32_e32 v126, v126
	v_exp_f32_e32 v127, v127
	v_pk_mul_f32 v[120:121], v[120:121], v[174:175]
	v_pk_mul_f32 v[112:113], v[112:113], v[168:169] op_sel_hi:[1,0]
	v_pk_mul_f32 v[122:123], v[122:123], v[168:169] op_sel_hi:[1,0]
	v_pk_mul_f32 v[120:121], v[112:113], v[120:121]
	v_add_f32_e32 v112, 1.0, v126
	v_add_f32_e32 v113, 1.0, v127
	v_mul_f32_e32 v126, 0xbfb8aa3b, v122
	v_mul_f32_e32 v127, 0xbfb8aa3b, v123
	v_exp_f32_e32 v126, v126
	v_exp_f32_e32 v127, v127
	v_rcp_f32_e32 v112, v112
	v_rcp_f32_e32 v113, v113
	v_add_f32_e32 v126, 1.0, v126
	v_add_f32_e32 v127, 1.0, v127
	v_rcp_f32_e32 v126, v126
	v_rcp_f32_e32 v127, v127
	v_pk_mul_f32 v[112:113], v[124:125], v[112:113]
	v_pk_mul_f32 v[118:119], v[118:119], v[168:169] op_sel_hi:[1,0]
	v_pk_mul_f32 v[114:115], v[114:115], v[168:169] op_sel_hi:[1,0]
	v_pk_mul_f32 v[118:119], v[118:119], v[112:113]
	v_pk_mul_f32 v[112:113], v[122:123], v[126:127]
	v_pk_mul_f32 v[108:109], v[108:109], v[170:171] op_sel_hi:[1,0]
	v_pk_mul_f32 v[122:123], v[114:115], v[112:113]
	v_cvt_pk_bf16_f32 v112, v116, v117
	v_mul_f32_e32 v116, 0xbfb8aa3b, v108
	v_mul_f32_e32 v117, 0xbfb8aa3b, v109
	v_exp_f32_e32 v116, v116
	v_exp_f32_e32 v117, v117
	v_mad_i64_i32 v[124:125], s[8:9], v166, s64, v[144:145]
	v_cvt_pk_bf16_f32 v113, v118, v119
	v_cvt_pk_bf16_f32 v114, v120, v121
	v_cvt_pk_bf16_f32 v115, v122, v123
	global_store_dwordx4 v[124:125], v[112:115], off
	v_pk_mul_f32 v[104:105], v[104:105], v[170:171] op_sel_hi:[1,0]
	v_pk_mul_f32 v[100:101], v[100:101], v[170:171] op_sel_hi:[1,0]
	v_add_f32_e32 v112, 1.0, v116
	v_add_f32_e32 v113, 1.0, v117
	v_rcp_f32_e32 v112, v112
	v_mul_f32_e32 v114, 0xbfb8aa3b, v104
	v_mul_f32_e32 v115, 0xbfb8aa3b, v105
	v_rcp_f32_e32 v113, v113
	v_exp_f32_e32 v114, v114
	v_exp_f32_e32 v115, v115
	v_pk_mul_f32 v[96:97], v[96:97], v[170:171] op_sel_hi:[1,0]
	v_pk_mul_f32 v[108:109], v[108:109], v[112:113]
	v_add_f32_e32 v114, 1.0, v114
	v_add_f32_e32 v115, 1.0, v115
	v_pk_mul_f32 v[100:101], v[100:101], v[108:109]
	v_pk_mul_f32 v[108:109], v[110:111], v[170:171] op_sel_hi:[1,0]
	v_rcp_f32_e32 v114, v114
	v_rcp_f32_e32 v115, v115
	v_mul_f32_e32 v110, 0xbfb8aa3b, v108
	v_mul_f32_e32 v111, 0xbfb8aa3b, v109
	v_exp_f32_e32 v110, v110
	v_exp_f32_e32 v111, v111
	v_pk_mul_f32 v[104:105], v[104:105], v[114:115]
	v_pk_mul_f32 v[106:107], v[106:107], v[170:171] op_sel_hi:[1,0]
	v_pk_mul_f32 v[104:105], v[96:97], v[104:105]
	v_add_f32_e32 v96, 1.0, v110
	v_add_f32_e32 v97, 1.0, v111
	v_mul_f32_e32 v110, 0xbfb8aa3b, v106
	v_mul_f32_e32 v111, 0xbfb8aa3b, v107
	v_exp_f32_e32 v110, v110
	v_exp_f32_e32 v111, v111
	v_rcp_f32_e32 v96, v96
	v_rcp_f32_e32 v97, v97
	v_add_f32_e32 v110, 1.0, v110
	v_add_f32_e32 v111, 1.0, v111
	v_rcp_f32_e32 v110, v110
	v_rcp_f32_e32 v111, v111
	v_pk_mul_f32 v[96:97], v[108:109], v[96:97]
	v_pk_mul_f32 v[102:103], v[102:103], v[170:171] op_sel_hi:[1,0]
	v_pk_mul_f32 v[98:99], v[98:99], v[170:171] op_sel_hi:[1,0]
	v_pk_mul_f32 v[102:103], v[102:103], v[96:97]
	v_pk_mul_f32 v[96:97], v[106:107], v[110:111]
	v_pk_mul_f32 v[92:93], v[92:93], v[162:163] op_sel_hi:[1,0]
	v_pk_mul_f32 v[106:107], v[98:99], v[96:97]
	v_cvt_pk_bf16_f32 v96, v100, v101
	v_mul_f32_e32 v100, 0xbfb8aa3b, v92
	v_mul_f32_e32 v101, 0xbfb8aa3b, v93
	v_exp_f32_e32 v100, v100
	v_exp_f32_e32 v101, v101
	v_mad_i64_i32 v[108:109], s[8:9], v160, s64, v[144:145]
	v_cvt_pk_bf16_f32 v97, v102, v103
	v_cvt_pk_bf16_f32 v98, v104, v105
	v_cvt_pk_bf16_f32 v99, v106, v107
	global_store_dwordx4 v[108:109], v[96:99], off
	v_pk_mul_f32 v[88:89], v[88:89], v[162:163] op_sel_hi:[1,0]
	v_pk_mul_f32 v[84:85], v[84:85], v[162:163] op_sel_hi:[1,0]
	v_add_f32_e32 v96, 1.0, v100
	v_add_f32_e32 v97, 1.0, v101
	v_rcp_f32_e32 v96, v96
	v_mul_f32_e32 v98, 0xbfb8aa3b, v88
	v_mul_f32_e32 v99, 0xbfb8aa3b, v89
	v_rcp_f32_e32 v97, v97
	v_exp_f32_e32 v98, v98
	v_exp_f32_e32 v99, v99
	v_pk_mul_f32 v[80:81], v[80:81], v[162:163] op_sel_hi:[1,0]
	v_pk_mul_f32 v[92:93], v[92:93], v[96:97]
	v_add_f32_e32 v98, 1.0, v98
	v_add_f32_e32 v99, 1.0, v99
	v_pk_mul_f32 v[84:85], v[84:85], v[92:93]
	v_pk_mul_f32 v[92:93], v[94:95], v[162:163] op_sel_hi:[1,0]
	v_rcp_f32_e32 v98, v98
	v_rcp_f32_e32 v99, v99
	v_mul_f32_e32 v94, 0xbfb8aa3b, v92
	v_mul_f32_e32 v95, 0xbfb8aa3b, v93
	v_exp_f32_e32 v94, v94
	v_exp_f32_e32 v95, v95
	v_pk_mul_f32 v[88:89], v[88:89], v[98:99]
	v_pk_mul_f32 v[90:91], v[90:91], v[162:163] op_sel_hi:[1,0]
	v_pk_mul_f32 v[88:89], v[80:81], v[88:89]
	v_add_f32_e32 v80, 1.0, v94
	v_add_f32_e32 v81, 1.0, v95
	v_mul_f32_e32 v94, 0xbfb8aa3b, v90
	v_mul_f32_e32 v95, 0xbfb8aa3b, v91
	v_exp_f32_e32 v94, v94
	v_exp_f32_e32 v95, v95
	v_rcp_f32_e32 v80, v80
	v_rcp_f32_e32 v81, v81
	v_add_f32_e32 v94, 1.0, v94
	v_add_f32_e32 v95, 1.0, v95
	v_rcp_f32_e32 v94, v94
	v_rcp_f32_e32 v95, v95
	v_pk_mul_f32 v[80:81], v[92:93], v[80:81]
	v_pk_mul_f32 v[86:87], v[86:87], v[162:163] op_sel_hi:[1,0]
	v_pk_mul_f32 v[82:83], v[82:83], v[162:163] op_sel_hi:[1,0]
	v_pk_mul_f32 v[86:87], v[86:87], v[80:81]
	v_pk_mul_f32 v[80:81], v[90:91], v[94:95]
	v_pk_mul_f32 v[76:77], v[76:77], v[158:159] op_sel_hi:[1,0]
	v_pk_mul_f32 v[90:91], v[82:83], v[80:81]
	v_cvt_pk_bf16_f32 v80, v84, v85
	v_mul_f32_e32 v84, 0xbfb8aa3b, v76
	v_mul_f32_e32 v85, 0xbfb8aa3b, v77
	v_exp_f32_e32 v84, v84
	v_exp_f32_e32 v85, v85
	v_mad_i64_i32 v[92:93], s[8:9], v156, s64, v[144:145]
	v_cvt_pk_bf16_f32 v81, v86, v87
	v_cvt_pk_bf16_f32 v82, v88, v89
	v_cvt_pk_bf16_f32 v83, v90, v91
	global_store_dwordx4 v[92:93], v[80:83], off
	v_pk_mul_f32 v[72:73], v[72:73], v[158:159] op_sel_hi:[1,0]
	v_pk_mul_f32 v[68:69], v[68:69], v[158:159] op_sel_hi:[1,0]
	v_add_f32_e32 v80, 1.0, v84
	v_add_f32_e32 v81, 1.0, v85
	v_rcp_f32_e32 v80, v80
	v_mul_f32_e32 v82, 0xbfb8aa3b, v72
	v_mul_f32_e32 v83, 0xbfb8aa3b, v73
	v_rcp_f32_e32 v81, v81
	v_exp_f32_e32 v82, v82
	v_exp_f32_e32 v83, v83
	v_pk_mul_f32 v[64:65], v[64:65], v[158:159] op_sel_hi:[1,0]
	v_pk_mul_f32 v[76:77], v[76:77], v[80:81]
	v_add_f32_e32 v82, 1.0, v82
	v_add_f32_e32 v83, 1.0, v83
	v_pk_mul_f32 v[68:69], v[68:69], v[76:77]
	v_pk_mul_f32 v[76:77], v[78:79], v[158:159] op_sel_hi:[1,0]
	v_rcp_f32_e32 v82, v82
	v_rcp_f32_e32 v83, v83
	v_mul_f32_e32 v78, 0xbfb8aa3b, v76
	v_mul_f32_e32 v79, 0xbfb8aa3b, v77
	v_exp_f32_e32 v78, v78
	v_exp_f32_e32 v79, v79
	v_pk_mul_f32 v[72:73], v[72:73], v[82:83]
	v_pk_mul_f32 v[74:75], v[74:75], v[158:159] op_sel_hi:[1,0]
	v_pk_mul_f32 v[72:73], v[64:65], v[72:73]
	v_add_f32_e32 v64, 1.0, v78
	v_add_f32_e32 v65, 1.0, v79
	v_mul_f32_e32 v78, 0xbfb8aa3b, v74
	v_mul_f32_e32 v79, 0xbfb8aa3b, v75
	v_exp_f32_e32 v78, v78
	v_exp_f32_e32 v79, v79
	v_rcp_f32_e32 v64, v64
	v_rcp_f32_e32 v65, v65
	v_add_f32_e32 v78, 1.0, v78
	v_add_f32_e32 v79, 1.0, v79
	v_rcp_f32_e32 v78, v78
	v_rcp_f32_e32 v79, v79
	v_pk_mul_f32 v[64:65], v[76:77], v[64:65]
	v_pk_mul_f32 v[70:71], v[70:71], v[158:159] op_sel_hi:[1,0]
	v_pk_mul_f32 v[66:67], v[66:67], v[158:159] op_sel_hi:[1,0]
	v_pk_mul_f32 v[70:71], v[70:71], v[64:65]
	v_pk_mul_f32 v[64:65], v[74:75], v[78:79]
	v_pk_mul_f32 v[60:61], v[60:61], v[154:155] op_sel_hi:[1,0]
	v_pk_mul_f32 v[74:75], v[66:67], v[64:65]
	v_cvt_pk_bf16_f32 v64, v68, v69
	v_mul_f32_e32 v68, 0xbfb8aa3b, v60
	v_mul_f32_e32 v69, 0xbfb8aa3b, v61
	v_exp_f32_e32 v68, v68
	v_exp_f32_e32 v69, v69
	v_mad_i64_i32 v[76:77], s[8:9], v152, s64, v[144:145]
	v_cvt_pk_bf16_f32 v65, v70, v71
	v_cvt_pk_bf16_f32 v66, v72, v73
	v_cvt_pk_bf16_f32 v67, v74, v75
	global_store_dwordx4 v[76:77], v[64:67], off
	v_pk_mul_f32 v[56:57], v[56:57], v[154:155] op_sel_hi:[1,0]
	v_pk_mul_f32 v[52:53], v[52:53], v[154:155] op_sel_hi:[1,0]
	v_add_f32_e32 v64, 1.0, v68
	v_add_f32_e32 v65, 1.0, v69
	v_rcp_f32_e32 v64, v64
	v_mul_f32_e32 v66, 0xbfb8aa3b, v56
	v_mul_f32_e32 v67, 0xbfb8aa3b, v57
	v_rcp_f32_e32 v65, v65
	v_exp_f32_e32 v66, v66
	v_exp_f32_e32 v67, v67
	v_pk_mul_f32 v[48:49], v[48:49], v[154:155] op_sel_hi:[1,0]
	v_pk_mul_f32 v[60:61], v[60:61], v[64:65]
	v_add_f32_e32 v66, 1.0, v66
	v_add_f32_e32 v67, 1.0, v67
	v_pk_mul_f32 v[52:53], v[52:53], v[60:61]
	v_pk_mul_f32 v[60:61], v[62:63], v[154:155] op_sel_hi:[1,0]
	v_rcp_f32_e32 v66, v66
	v_rcp_f32_e32 v67, v67
	v_mul_f32_e32 v62, 0xbfb8aa3b, v60
	v_mul_f32_e32 v63, 0xbfb8aa3b, v61
	v_exp_f32_e32 v62, v62
	v_exp_f32_e32 v63, v63
	v_pk_mul_f32 v[56:57], v[56:57], v[66:67]
	v_pk_mul_f32 v[58:59], v[58:59], v[154:155] op_sel_hi:[1,0]
	v_pk_mul_f32 v[56:57], v[48:49], v[56:57]
	v_add_f32_e32 v48, 1.0, v62
	v_add_f32_e32 v49, 1.0, v63
	v_mul_f32_e32 v62, 0xbfb8aa3b, v58
	v_mul_f32_e32 v63, 0xbfb8aa3b, v59
	v_exp_f32_e32 v62, v62
	v_exp_f32_e32 v63, v63
	v_rcp_f32_e32 v48, v48
	v_rcp_f32_e32 v49, v49
	v_add_f32_e32 v62, 1.0, v62
	v_add_f32_e32 v63, 1.0, v63
	v_rcp_f32_e32 v62, v62
	v_rcp_f32_e32 v63, v63
	v_pk_mul_f32 v[48:49], v[60:61], v[48:49]
	v_pk_mul_f32 v[54:55], v[54:55], v[154:155] op_sel_hi:[1,0]
	v_pk_mul_f32 v[50:51], v[50:51], v[154:155] op_sel_hi:[1,0]
	v_pk_mul_f32 v[54:55], v[54:55], v[48:49]
	v_pk_mul_f32 v[48:49], v[58:59], v[62:63]
	v_pk_mul_f32 v[44:45], v[44:45], v[150:151] op_sel_hi:[1,0]
	v_pk_mul_f32 v[58:59], v[50:51], v[48:49]
	v_cvt_pk_bf16_f32 v48, v52, v53
	v_mul_f32_e32 v52, 0xbfb8aa3b, v44
	v_mul_f32_e32 v53, 0xbfb8aa3b, v45
	v_exp_f32_e32 v52, v52
	v_exp_f32_e32 v53, v53
	v_mad_i64_i32 v[60:61], s[8:9], v165, s64, v[144:145]
	v_cvt_pk_bf16_f32 v49, v54, v55
	v_cvt_pk_bf16_f32 v50, v56, v57
	v_cvt_pk_bf16_f32 v51, v58, v59
	global_store_dwordx4 v[60:61], v[48:51], off
	v_pk_mul_f32 v[40:41], v[40:41], v[150:151] op_sel_hi:[1,0]
	v_pk_mul_f32 v[36:37], v[36:37], v[150:151] op_sel_hi:[1,0]
	v_add_f32_e32 v48, 1.0, v52
	v_add_f32_e32 v49, 1.0, v53
	v_rcp_f32_e32 v48, v48
	v_mul_f32_e32 v50, 0xbfb8aa3b, v40
	v_mul_f32_e32 v51, 0xbfb8aa3b, v41
	v_rcp_f32_e32 v49, v49
	v_exp_f32_e32 v50, v50
	v_exp_f32_e32 v51, v51
	v_pk_mul_f32 v[32:33], v[32:33], v[150:151] op_sel_hi:[1,0]
	v_pk_mul_f32 v[44:45], v[44:45], v[48:49]
	v_add_f32_e32 v50, 1.0, v50
	v_add_f32_e32 v51, 1.0, v51
	v_pk_mul_f32 v[36:37], v[36:37], v[44:45]
	v_pk_mul_f32 v[44:45], v[46:47], v[150:151] op_sel_hi:[1,0]
	v_rcp_f32_e32 v50, v50
	v_rcp_f32_e32 v51, v51
	v_mul_f32_e32 v46, 0xbfb8aa3b, v44
	v_mul_f32_e32 v47, 0xbfb8aa3b, v45
	v_exp_f32_e32 v46, v46
	v_exp_f32_e32 v47, v47
	v_pk_mul_f32 v[40:41], v[40:41], v[50:51]
	v_pk_mul_f32 v[42:43], v[42:43], v[150:151] op_sel_hi:[1,0]
	v_pk_mul_f32 v[40:41], v[32:33], v[40:41]
	v_add_f32_e32 v32, 1.0, v46
	v_add_f32_e32 v33, 1.0, v47
	v_mul_f32_e32 v46, 0xbfb8aa3b, v42
	v_mul_f32_e32 v47, 0xbfb8aa3b, v43
	v_exp_f32_e32 v46, v46
	v_exp_f32_e32 v47, v47
	v_rcp_f32_e32 v32, v32
	v_rcp_f32_e32 v33, v33
	v_add_f32_e32 v46, 1.0, v46
	v_add_f32_e32 v47, 1.0, v47
	v_rcp_f32_e32 v46, v46
	v_rcp_f32_e32 v47, v47
	v_pk_mul_f32 v[32:33], v[44:45], v[32:33]
	v_pk_mul_f32 v[38:39], v[38:39], v[150:151] op_sel_hi:[1,0]
	v_pk_mul_f32 v[34:35], v[34:35], v[150:151] op_sel_hi:[1,0]
	v_pk_mul_f32 v[38:39], v[38:39], v[32:33]
	v_pk_mul_f32 v[32:33], v[42:43], v[46:47]
	v_pk_mul_f32 v[28:29], v[28:29], v[148:149] op_sel_hi:[1,0]
	v_pk_mul_f32 v[42:43], v[34:35], v[32:33]
	v_cvt_pk_bf16_f32 v32, v36, v37
	v_mul_f32_e32 v36, 0xbfb8aa3b, v28
	v_mul_f32_e32 v37, 0xbfb8aa3b, v29
	v_exp_f32_e32 v36, v36
	v_exp_f32_e32 v37, v37
	v_mad_i64_i32 v[44:45], s[8:9], v161, s64, v[144:145]
; #define PG8_BAR __builtin_amdgcn_s_barrier()
; template <class Epi, class Sched, bool ALIGN_EPI = false, bool SP2 = false>
; __device__ __forceinline__ void gemm_phase(LAS unsigned char* lds, const Gemm g, const Sched S, const Epi E) {
;     ...
;         if (!has_next) break;
; #pragma unroll
;         for (int a = 0; a < 2; ++a)
; #pragma unroll
;             for (int b = 0; b < 2; ++b)
; #pragma unroll
;                 for (int m = 0; m < 4; ++m)
; #pragma unroll
;                     for (int n = 0; n < 2; ++n) acc[a][b][m][n] = (f32x4){0.f, 0.f, 0.f, 0.f};
;         cur = nxt; cA = nA; cB = nB; ++ui;
;         if constexpr (ALIGN_EPI) { if (wr == 1) PG8_BAR; }
	v_cvt_pk_bf16_f32 v33, v38, v39
	v_cvt_pk_bf16_f32 v34, v40, v41
	v_cvt_pk_bf16_f32 v35, v42, v43
	global_store_dwordx4 v[44:45], v[32:35], off
	v_pk_mul_f32 v[24:25], v[24:25], v[148:149] op_sel_hi:[1,0]
	v_pk_mul_f32 v[20:21], v[20:21], v[148:149] op_sel_hi:[1,0]
	v_add_f32_e32 v32, 1.0, v36
	v_add_f32_e32 v33, 1.0, v37
	v_rcp_f32_e32 v32, v32
	v_mul_f32_e32 v34, 0xbfb8aa3b, v24
	v_mul_f32_e32 v35, 0xbfb8aa3b, v25
	v_rcp_f32_e32 v33, v33
	v_exp_f32_e32 v34, v34
	v_exp_f32_e32 v35, v35
	v_pk_mul_f32 v[16:17], v[16:17], v[148:149] op_sel_hi:[1,0]
	v_pk_mul_f32 v[28:29], v[28:29], v[32:33]
	v_add_f32_e32 v34, 1.0, v34
	v_add_f32_e32 v35, 1.0, v35
	v_pk_mul_f32 v[20:21], v[20:21], v[28:29]
	v_pk_mul_f32 v[28:29], v[30:31], v[148:149] op_sel_hi:[1,0]
	v_rcp_f32_e32 v34, v34
	v_rcp_f32_e32 v35, v35
	v_mul_f32_e32 v30, 0xbfb8aa3b, v28
	v_mul_f32_e32 v31, 0xbfb8aa3b, v29
	v_exp_f32_e32 v30, v30
	v_exp_f32_e32 v31, v31
	v_pk_mul_f32 v[24:25], v[24:25], v[34:35]
	v_pk_mul_f32 v[26:27], v[26:27], v[148:149] op_sel_hi:[1,0]
	v_pk_mul_f32 v[24:25], v[16:17], v[24:25]
	v_add_f32_e32 v16, 1.0, v30
	v_add_f32_e32 v17, 1.0, v31
	v_mul_f32_e32 v30, 0xbfb8aa3b, v26
	v_mul_f32_e32 v31, 0xbfb8aa3b, v27
	v_exp_f32_e32 v30, v30
	v_exp_f32_e32 v31, v31
	v_rcp_f32_e32 v16, v16
	v_rcp_f32_e32 v17, v17
	v_add_f32_e32 v30, 1.0, v30
	v_add_f32_e32 v31, 1.0, v31
	v_rcp_f32_e32 v30, v30
	v_rcp_f32_e32 v31, v31
	v_pk_mul_f32 v[16:17], v[28:29], v[16:17]
	v_pk_mul_f32 v[22:23], v[22:23], v[148:149] op_sel_hi:[1,0]
	v_pk_mul_f32 v[18:19], v[18:19], v[148:149] op_sel_hi:[1,0]
	v_pk_mul_f32 v[22:23], v[22:23], v[16:17]
	v_pk_mul_f32 v[16:17], v[26:27], v[30:31]
	v_pk_mul_f32 v[12:13], v[12:13], v[146:147] op_sel_hi:[1,0]
	v_pk_mul_f32 v[26:27], v[18:19], v[16:17]
	v_cvt_pk_bf16_f32 v16, v20, v21
	v_mul_f32_e32 v20, 0xbfb8aa3b, v12
	v_mul_f32_e32 v21, 0xbfb8aa3b, v13
	v_exp_f32_e32 v20, v20
	v_exp_f32_e32 v21, v21
	v_mad_i64_i32 v[28:29], s[8:9], v157, s64, v[144:145]
	v_cvt_pk_bf16_f32 v17, v22, v23
	v_cvt_pk_bf16_f32 v18, v24, v25
	v_cvt_pk_bf16_f32 v19, v26, v27
	global_store_dwordx4 v[28:29], v[16:19], off
	v_pk_mul_f32 v[8:9], v[8:9], v[146:147] op_sel_hi:[1,0]
	v_pk_mul_f32 v[4:5], v[4:5], v[146:147] op_sel_hi:[1,0]
	v_add_f32_e32 v16, 1.0, v20
	v_add_f32_e32 v17, 1.0, v21
	v_rcp_f32_e32 v16, v16
	v_mul_f32_e32 v18, 0xbfb8aa3b, v8
	v_mul_f32_e32 v19, 0xbfb8aa3b, v9
	v_rcp_f32_e32 v17, v17
	v_exp_f32_e32 v18, v18
	v_exp_f32_e32 v19, v19
	v_pk_mul_f32 v[0:1], v[0:1], v[146:147] op_sel_hi:[1,0]
	v_pk_mul_f32 v[12:13], v[12:13], v[16:17]
	v_add_f32_e32 v18, 1.0, v18
	v_add_f32_e32 v19, 1.0, v19
	v_pk_mul_f32 v[4:5], v[4:5], v[12:13]
	v_pk_mul_f32 v[12:13], v[14:15], v[146:147] op_sel_hi:[1,0]
	v_rcp_f32_e32 v18, v18
	v_rcp_f32_e32 v19, v19
	v_mul_f32_e32 v14, 0xbfb8aa3b, v12
	v_mul_f32_e32 v15, 0xbfb8aa3b, v13
	v_exp_f32_e32 v14, v14
	v_exp_f32_e32 v15, v15
	v_pk_mul_f32 v[8:9], v[8:9], v[18:19]
	v_pk_mul_f32 v[10:11], v[10:11], v[146:147] op_sel_hi:[1,0]
	v_pk_mul_f32 v[8:9], v[0:1], v[8:9]
	v_add_f32_e32 v0, 1.0, v14
	v_add_f32_e32 v1, 1.0, v15
	v_mul_f32_e32 v14, 0xbfb8aa3b, v10
	v_mul_f32_e32 v15, 0xbfb8aa3b, v11
	v_exp_f32_e32 v14, v14
	v_exp_f32_e32 v15, v15
	v_rcp_f32_e32 v0, v0
	v_rcp_f32_e32 v1, v1
	v_add_f32_e32 v14, 1.0, v14
	v_add_f32_e32 v15, 1.0, v15
	v_rcp_f32_e32 v14, v14
	v_rcp_f32_e32 v15, v15
	v_pk_mul_f32 v[0:1], v[12:13], v[0:1]
	v_pk_mul_f32 v[6:7], v[6:7], v[146:147] op_sel_hi:[1,0]
	v_pk_mul_f32 v[2:3], v[2:3], v[146:147] op_sel_hi:[1,0]
	v_pk_mul_f32 v[6:7], v[6:7], v[0:1]
	v_pk_mul_f32 v[0:1], v[10:11], v[14:15]
	v_mad_i64_i32 v[12:13], s[8:9], v153, s64, v[144:145]
	v_pk_mul_f32 v[10:11], v[2:3], v[0:1]
	v_cvt_pk_bf16_f32 v0, v4, v5
	v_cvt_pk_bf16_f32 v1, v6, v7
	v_cvt_pk_bf16_f32 v2, v8, v9
	v_cvt_pk_bf16_f32 v3, v10, v11
	s_andn2_b64 vcc, exec, s[6:7]
	s_mov_b64 s[6:7], -1
	global_store_dwordx4 v[12:13], v[0:3], off
	s_cbranch_vccnz .LBB0_1846
	s_andn2_b64 vcc, exec, s[44:45]
	s_cbranch_vccnz .LBB0_1845
	s_barrier
	s_branch .LBB0_1845

; __global__ void __launch_bounds__(512, 2) mega(Params p) {
	.amdhsa_kernel _Z4mega6Params
		.amdhsa_group_segment_fixed_size 0
		.amdhsa_private_segment_fixed_size 0
		.amdhsa_kernarg_size 592
		.amdhsa_user_sgpr_count 2
		.amdhsa_user_sgpr_dispatch_ptr 0
		.amdhsa_user_sgpr_queue_ptr 0
		.amdhsa_user_sgpr_kernarg_segment_ptr 1
		.amdhsa_user_sgpr_dispatch_id 0
		.amdhsa_user_sgpr_kernarg_preload_length 0
		.amdhsa_user_sgpr_kernarg_preload_offset 0
		.amdhsa_user_sgpr_private_segment_size 0
		.amdhsa_uses_dynamic_stack 0
		.amdhsa_enable_private_segment 0
		.amdhsa_system_sgpr_workgroup_id_x 1
		.amdhsa_system_sgpr_workgroup_id_y 0
		.amdhsa_system_sgpr_workgroup_id_z 0
		.amdhsa_system_sgpr_workgroup_info 0
		.amdhsa_system_vgpr_workitem_id 2
		.amdhsa_next_free_vgpr 256
		.amdhsa_next_free_sgpr 102
		.amdhsa_accum_offset 256
		.amdhsa_reserve_vcc 1
		.amdhsa_float_round_mode_32 0
		.amdhsa_float_round_mode_16_64 0
		.amdhsa_float_denorm_mode_32 3
		.amdhsa_float_denorm_mode_16_64 3
		.amdhsa_dx10_clamp 1
		.amdhsa_ieee_mode 1
		.amdhsa_fp16_overflow 0
		.amdhsa_tg_split 0
		.amdhsa_exception_fp_ieee_invalid_op 0
		.amdhsa_exception_fp_denorm_src 0
		.amdhsa_exception_fp_ieee_div_zero 0
		.amdhsa_exception_fp_ieee_overflow 0
		.amdhsa_exception_fp_ieee_underflow 0
		.amdhsa_exception_fp_ieee_inexact 0
		.amdhsa_exception_int_div_zero 0
	.end_amdhsa_kernel

; __global__ void __launch_bounds__(512, 2) mega(Params p) {
amdhsa.kernels:
  - .agpr_count:     0
    .args:
      - .offset:         0
        .size:           336
        .value_kind:     by_value
      - .offset:         336
        .size:           4
        .value_kind:     hidden_block_count_x
      - .offset:         340
        .size:           4
        .value_kind:     hidden_block_count_y
      - .offset:         344
        .size:           4
        .value_kind:     hidden_block_count_z
      - .offset:         348
        .size:           2
        .value_kind:     hidden_group_size_x
      - .offset:         350
        .size:           2
        .value_kind:     hidden_group_size_y
      - .offset:         352
        .size:           2
        .value_kind:     hidden_group_size_z
      - .offset:         354
        .size:           2
        .value_kind:     hidden_remainder_x
      - .offset:         356
        .size:           2
        .value_kind:     hidden_remainder_y
      - .offset:         358
        .size:           2
        .value_kind:     hidden_remainder_z
      - .offset:         376
        .size:           8
        .value_kind:     hidden_global_offset_x
      - .offset:         384
        .size:           8
        .value_kind:     hidden_global_offset_y
      - .offset:         392
        .size:           8
        .value_kind:     hidden_global_offset_z
      - .offset:         400
        .size:           2
        .value_kind:     hidden_grid_dims
      - .offset:         424
        .size:           8
        .value_kind:     hidden_multigrid_sync_arg
      - .offset:         456
        .size:           4
        .value_kind:     hidden_dynamic_lds_size
    .group_segment_fixed_size: 0
    .kernarg_segment_align: 8
    .kernarg_segment_size: 592
    .language:       OpenCL C
    .language_version:
      - 2
      - 0
    .max_flat_workgroup_size: 512
    .name:           _Z4mega6Params
    .private_segment_fixed_size: 0
    .sgpr_count:     108
    .sgpr_spill_count: 16
    .symbol:         _Z4mega6Params.kd
    .uniform_work_group_size: 1
    .uses_dynamic_stack: false
    .vgpr_count:     256
    .vgpr_spill_count: 0
    .wavefront_size: 64
